# split grid barrier after phase 0 too: first item round (all modulation GEMV tiles), arrive, copy of the item loop for the remaining weight-transpose rounds, wait before the phase-1 row op; plus the 5-
# speedup vs baseline: 1.0085x; 1.0029x over previous
.LBB0_21:
	s_or_b64 exec, exec, s[20:21]
	s_waitcnt lgkmcnt(0)
	s_load_dword s4, s[18:19], 0x0
	s_waitcnt lgkmcnt(0)
	s_lshl_b32 s4, s4, 1
	s_add_i32 s33, s4, s33
	s_cmp_lt_i32 s33, s4
	s_cbranch_scc0 .LBB0_71

.LBB0_126:
	s_cmp_lt_i32 s88, 1
	s_cbranch_scc0 .Lp0_done
	s_cmp_gt_i32 s89, 0
	s_cbranch_scc0 .Lp0_done
	s_load_dword s4, s[0:1], 0x120
	s_load_dwordx16 s[52:67], s[0:1], 0x0
	s_load_dwordx16 s[68:83], s[0:1], 0x80
	s_waitcnt lgkmcnt(0)
	s_lshl_b32 s4, s4, 1
	s_lshl_b32 s33, s2, 1
	s_add_i32 s33, s33, s4
	s_cmpk_gt_i32 s33, 0x15cf
	s_cbranch_scc1 .Lp0_done
	s_add_u32 s94, s34, 0x1da0000
	s_addc_u32 s95, s35, 0
	v_writelane_b32 v252, s90, 0
	s_add_u32 s4, s34, 0x7a0000
	s_addc_u32 s5, s35, 0
	v_writelane_b32 v252, s91, 1
	v_writelane_b32 v252, s4, 2
	v_lshrrev_b32_e32 v138, 8, v204
	v_and_b32_e32 v139, 0xff, v204
	v_writelane_b32 v252, s5, 3
	s_add_u32 s4, s34, 0x720000
	s_addc_u32 s5, s35, 0
	v_writelane_b32 v252, s4, 4
	v_mul_u32_u24_e32 v140, 0x12000, v138
	v_mov_b32_e32 v129, 0
	v_writelane_b32 v252, s5, 5
	s_add_u32 s4, s34, 0x520000
	s_addc_u32 s5, s35, 0
	s_add_u32 s90, s34, 0x4a0000
	s_addc_u32 s91, s35, 0
	s_add_u32 s96, s34, 0x440000
	s_addc_u32 s97, s35, 0
	s_add_u32 s16, s34, 0x28a0000
	s_addc_u32 s17, s35, 0
	s_add_u32 s18, s0, 0x120
	v_writelane_b32 v252, s4, 6
	s_addc_u32 s19, s1, 0
	s_movk_i32 s8, 0x104
	s_movk_i32 s9, 0xffe0
	s_movk_i32 s10, 0x6000
	s_movk_i32 s11, 0x400
	s_mov_b32 s12, 0xbfb8aa3b
	s_mov_b32 s13, 0x42ce8ed0
	s_mov_b32 s14, 0xc2b17218
	s_movk_i32 s15, 0x1800
	v_mov_b32_e32 v141, 0xfffffd40
	v_mov_b32_e32 v142, 0xb00000
	v_mov_b32_e32 v143, 0x580000
	v_mov_b32_e32 v144, 0x7f800000
	v_writelane_b32 v252, s5, 7
	s_branch .Lp0c_22

.Lp0_done:
	s_cmp_gt_i32 s88, 0
	s_cbranch_scc1 .Lsb0_skip
	s_cmp_lt_i32 s89, 2
	s_cbranch_scc1 .Lsb0_skip
	s_waitcnt vmcnt(0) lgkmcnt(0)
	s_and_saveexec_b64 s[16:17], s[92:93]
	s_cbranch_execz .Lsb0_done
	v_mov_b32_e32 v0, 0x24008
	ds_read_b32 v1, v0
	buffer_inv sc1
	s_add_u32 s18, s34, 0xed10500
	s_addc_u32 s19, s35, 0
	v_mov_b32_e32 v0, 0
	s_mov_b32 s20, 0
	s_waitcnt lgkmcnt(0)

.Lsb0_skip:
	s_cmp_gt_i32 s89, 1
	s_cselect_b64 s[4:5], -1, 0
	s_waitcnt lgkmcnt(0)
	s_cmp_lt_i32 s88, 2
	s_cselect_b64 s[6:7], -1, 0
	s_and_b64 s[4:5], s[6:7], s[4:5]
	s_andn2_b64 vcc, exec, s[4:5]
	v_lshrrev_b32_e32 v205, 6, v204
	s_cbranch_vccnz .LBB0_135
	v_lshl_add_u32 v4, s2, 3, v205
	s_movk_i32 s4, 0x2000
	v_cmp_gt_i32_e32 vcc, s4, v4
	s_and_saveexec_b64 s[8:9], vcc
	s_cbranch_execz .LBB0_134
	v_mbcnt_lo_u32_b32 v1, -1, 0
	v_mbcnt_hi_u32_b32 v1, -1, v1
	v_and_b32_e32 v2, 64, v1
	v_add_u32_e32 v2, 64, v2
	v_xor_b32_e32 v3, 32, v1
	v_cmp_lt_i32_e32 vcc, v3, v2
	s_load_dwordx16 s[16:31], s[0:1], 0x40
	s_load_dword s4, s[0:1], 0x120
	v_cndmask_b32_e32 v3, v1, v3, vcc
	v_lshlrev_b32_e32 v20, 2, v3
	v_xor_b32_e32 v3, 16, v1
	v_cmp_lt_i32_e32 vcc, v3, v2
	v_lshlrev_b32_e32 v0, 2, v204
	v_and_b32_e32 v0, 0xfc, v0
	v_cndmask_b32_e32 v3, v1, v3, vcc
	v_lshlrev_b32_e32 v21, 2, v3
	v_xor_b32_e32 v3, 8, v1
	v_cmp_lt_i32_e32 vcc, v3, v2
	v_mov_b32_e32 v7, 0
	v_lshlrev_b32_e32 v6, 2, v0
	v_cndmask_b32_e32 v3, v1, v3, vcc
	v_lshlrev_b32_e32 v22, 2, v3
	v_xor_b32_e32 v3, 4, v1
	v_cmp_lt_i32_e32 vcc, v3, v2
	s_add_u32 s10, s34, 0x28a0000
	s_waitcnt lgkmcnt(0)
	v_lshl_add_u64 v[8:9], s[20:21], 0, v[6:7]
	v_cndmask_b32_e32 v3, v1, v3, vcc
	v_lshlrev_b32_e32 v23, 2, v3
	v_xor_b32_e32 v3, 2, v1
	v_cmp_lt_i32_e32 vcc, v3, v2
	v_lshlrev_b32_e32 v6, 1, v0
	s_addc_u32 s11, s35, 0
	v_cndmask_b32_e32 v3, v1, v3, vcc
	v_lshlrev_b32_e32 v24, 2, v3
	v_xor_b32_e32 v3, 1, v1
	v_cmp_lt_i32_e32 vcc, v3, v2
	s_lshl_b32 s14, s4, 3
	v_or_b32_e32 v2, 0x100, v0
	v_cndmask_b32_e32 v1, v1, v3, vcc
	v_or_b32_e32 v16, 0x200, v0
	v_or_b32_e32 v18, 0x300, v0
	v_lshl_add_u64 v[10:11], s[34:35], 0, v[6:7]
	s_mov_b64 s[4:5], 0x8a44000
	v_lshlrev_b32_e32 v25, 2, v1
	v_lshl_add_u64 v[10:11], v[10:11], 0, s[4:5]
	s_mov_b64 s[12:13], 0
	s_movk_i32 s15, 0x1000
	s_movk_i32 s18, 0xfff
	s_movk_i32 s19, 0x1800
	v_lshlrev_b32_e32 v12, 2, v0
	v_mov_b32_e32 v13, v7
	v_mov_b32_e32 v26, 0x358637bd
	s_mov_b32 s20, 0x800000
	s_mov_b64 s[16:17], 0x1000
	v_lshlrev_b32_e32 v14, 2, v2
	v_mov_b32_e32 v15, v7
	v_lshlrev_b32_e32 v16, 2, v16
	v_mov_b32_e32 v17, v7
	v_lshlrev_b32_e32 v18, 2, v18
	v_mov_b32_e32 v19, v7
	s_movk_i32 s21, 0x1fff
	s_branch .LBB0_130
